# prep weight-tile loads nt as well (streamed once)
# speedup vs baseline: 1.0050x; 1.0003x over previous
.LBB0_25:
	s_cmp_gt_i32 s6, -1
	s_cselect_b64 s[28:29], -1, 0
	s_lshl_b32 s27, s34, 6
	s_lshl_b64 s[34:35], s[6:7], 2
	s_add_u32 s0, s0, s34
	s_addc_u32 s1, s1, s35
	v_mov_b32_e32 v145, v35
	v_lshl_add_u64 v[2:3], s[0:1], 0, v[144:145]
	v_or_b32_e32 v4, s27, v175
	v_mad_u64_u32 v[8:9], s[34:35], s26, v4, 0
	s_lshl_b32 s0, s26, 5
	s_mov_b32 s1, 0
	v_lshl_add_u64 v[8:9], v[8:9], 2, v[2:3]
	s_andn2_b64 vcc, exec, s[28:29]
	s_cbranch_vccnz .Lpz_zero
	global_load_dword v10, v[8:9], off nt
	v_lshl_add_u64 v[8:9], v[8:9], 0, s[0:1]
	global_load_dword v11, v[8:9], off nt
	v_lshl_add_u64 v[8:9], v[8:9], 0, s[0:1]
	global_load_dword v12, v[8:9], off nt
	v_lshl_add_u64 v[8:9], v[8:9], 0, s[0:1]
	global_load_dword v13, v[8:9], off nt
	v_lshl_add_u64 v[8:9], v[8:9], 0, s[0:1]
	global_load_dword v14, v[8:9], off nt
	v_lshl_add_u64 v[8:9], v[8:9], 0, s[0:1]
	global_load_dword v15, v[8:9], off nt
	v_lshl_add_u64 v[8:9], v[8:9], 0, s[0:1]
	global_load_dword v16, v[8:9], off nt
	v_lshl_add_u64 v[8:9], v[8:9], 0, s[0:1]
	global_load_dword v17, v[8:9], off nt
	s_waitcnt vmcnt(0)
	s_branch .Lpz_store
